# v19 + refined layer-3 (G=256) G1 tile-order table found by hill-climb
# baseline (speedup 1.0000x reference)
.LBB0_313:
	s_and_b64 vcc, exec, s[0:1]
	s_cbranch_vccz .LBB0_422
	s_cmpk_lt_i32 s2, 0x420
	v_mov_b32_e32 v8, v209
	s_mov_b32 s4, s81
	s_cselect_b64 s[0:1], -1, 0
	s_cmpk_gt_i32 s2, 0x41f
	s_cbranch_scc1 .LBB0_316
	s_ashr_i32 s5, s2, 31
	s_lshr_b32 s5, s5, 29
	s_add_i32 s5, s2, s5
	s_ashr_i32 s6, s5, 3
	s_and_b32 s5, s5, -8
	s_sub_i32 s5, s2, s5
	s_cmp_lt_i32 s5, 0
	s_movk_i32 s7, 0x85
	s_cselect_b32 s7, s7, 0x84
	s_mul_i32 s5, s5, s7
	s_add_i32 s5, s5, s6
	s_mul_hi_i32 s6, s5, 0x2e8ba2e9
	s_lshr_b32 s7, s6, 31
	s_ashr_i32 s6, s6, 5
	s_add_i32 s6, s6, s7
	s_lshl_b32 s7, s6, 3
	s_mulk_i32 s6, 0xb0
	s_sub_i32 s5, s5, s6
	s_bfe_u32 s6, s5, 0x3001c
	s_add_i32 s6, s5, s6
	s_sext_i32_i16 s8, s6
	s_and_b32 s6, s6, 0xfff8
	s_sub_i32 s6, s5, s6
	s_ashr_i32 s8, s8, 3
	s_sext_i32_i16 s6, s6
	s_add_i32 s38, s7, s6
	s_mul_i32 s8, s8, 5
	s_cmpk_lt_i32 s5, 0x60
	s_sext_i32_i16 s5, s8
	s_cselect_b64 s[6:7], -1, 0
	s_sub_i32 s8, s5, 60
	s_cmpk_eq_i32 s57, 0xd8
	s_mov_b32 s9, 0x5074a873
	s_mov_b32 s10, 0x251a3
	s_mov_b32 s11, 0x96c0bdd0
	s_mov_b32 s12, 0x292a201
	s_cselect_b32 s9, s9, 0x98f3c68b
	s_cselect_b32 s10, s10, 0x709c
	s_cselect_b32 s11, s11, 0xaa6410a1
	s_cselect_b32 s12, s12, 0x244a6b
	s_and_b64 s[6:7], s[6:7], exec
	s_cselect_b32 s5, s5, s8
	s_cselect_b32 s7, s12, s10
	s_cselect_b32 s6, s11, s9
	s_lshr_b64 s[6:7], s[6:7], s5
	s_and_b32 s58, s6, 31

.LBB0_319:
	v_readlane_b32 s20, v254, 19
	v_readlane_b32 s21, v254, 20
	s_add_u32 s48, s20, 0x39a00000
	s_addc_u32 s49, s21, 0
	s_add_u32 s78, s20, 0x3e200000
	s_addc_u32 s79, s21, 0
	s_add_u32 s82, s20, 0x3fa00000
	s_addc_u32 s83, s21, 0
	s_add_u32 s86, s20, 0x41200000
	s_addc_u32 s87, s21, 0
	s_add_u32 s90, s20, 0x42a00000
	s_addc_u32 s91, s21, 0
	s_add_u32 s94, s20, 0x44200000
	s_addc_u32 s95, s21, 0
	s_add_u32 s6, s20, 0x28c00000
	s_addc_u32 s7, s21, 0
	v_writelane_b32 v254, s6, 29
	v_readlane_b32 s16, v253, 63
	s_lshl_b32 s8, s65, 10
	v_writelane_b32 v254, s7, 30
	v_lshl_add_u64 v[6:7], v[6:7], 0, s[96:97]
	v_readlane_b32 s17, v254, 0
	s_mov_b32 s1, s17
	v_readlane_b32 s18, v254, 1
	v_readlane_b32 s19, v254, 2
	s_mov_b32 s9, s17
	v_writelane_b32 v253, s0, 63
	s_lshl_b64 s[6:7], s[8:9], 2
	s_waitcnt vmcnt(2)
	s_barrier
	v_writelane_b32 v254, s1, 0
	v_writelane_b32 v254, s2, 1
	v_writelane_b32 v254, s3, 2
	s_add_u32 s1, s20, s6
	s_addc_u32 s5, s21, s7
	s_add_u32 s6, s1, 0x200000
	s_addc_u32 s7, s5, 0
	s_and_b32 s5, s4, 3
	s_add_i32 m0, s59, 0x18000
	v_writelane_b32 v254, s6, 31
	s_lshl_b32 s11, s0, 6
	s_lshl_b32 s15, s5, 5
	global_load_lds_dwordx4 v[6:7], off
	v_lshl_add_u64 v[4:5], v[4:5], 0, s[96:97]
	s_add_i32 m0, s59, 0x1a000
	s_add_i32 s12, s59, 0x8000
	s_add_i32 s13, s59, 0xa000
	v_writelane_b32 v254, s7, 32
	global_load_lds_dwordx4 v[4:5], off
	v_lshl_add_u64 v[0:1], v[0:1], 0, s[96:97]
	s_mov_b32 m0, s12
	s_add_u32 s6, s24, 0x80080
	global_load_lds_dwordx4 v[0:1], off
	v_lshl_add_u64 v[0:1], v[2:3], 0, s[96:97]
	s_mov_b32 m0, s13
	s_addc_u32 s7, s25, 0
	global_load_lds_dwordx4 v[0:1], off
	s_add_i32 m0, s59, 0x1c000
	v_lshl_add_u64 v[0:1], s[6:7], 0, v[174:175]
	global_load_lds_dwordx4 v[0:1], off
	v_lshl_add_u64 v[0:1], s[6:7], 0, v[176:177]
	s_add_i32 m0, s59, 0x1e000
	s_cmp_lt_u32 s4, 4
	global_load_lds_dwordx4 v[0:1], off
	v_and_b32_e32 v1, 0xfffffc00, v15
	v_lshl_add_u32 v2, s0, 13, v1
	v_lshl_add_u32 v1, s5, 12, v1
	s_cselect_b64 s[0:1], -1, 0
	s_lshl_b32 s5, s5, 4
	s_mov_b32 s35, s5
	s_or_b32 s5, s5, s15
	s_and_b32 s5, s5, 0x50
	v_writelane_b32 v254, s5, 33
	s_bfe_u32 s5, s4, 0x10001
	v_writelane_b32 v254, s5, 35
	s_and_b32 s4, s4, 1
	v_writelane_b32 v254, s4, 36
	s_and_b32 s4, s15, 32
	s_ashr_i32 s33, s57, 31
	s_ashr_i32 s84, s2, 31
	v_writelane_b32 v254, s4, 37
	s_cmpk_eq_i32 s57, 0xd8
	s_mov_b32 s4, 0x251a3
	s_cselect_b32 s4, s4, 0x709c
	v_writelane_b32 v254, s4, 38
	s_mov_b32 s4, 0x5074a873
	s_cselect_b32 s4, s4, 0x98f3c68b
	v_writelane_b32 v254, s4, 39
	s_mov_b32 s4, 0x292a201
	v_and_b32_e32 v65, 15, v8
	v_and_b32_e32 v0, 48, v8
	v_lshlrev_b32_e32 v3, 2, v8
	s_cselect_b32 s4, s4, 0x244a6b
	v_lshl_or_b32 v0, v65, 6, v0
	v_and_b32_e32 v3, 32, v3
	v_writelane_b32 v254, s4, 40
	s_mov_b32 s4, 0x96c0bdd0
	v_bitop3_b32 v2, v0, v2, v3 bitop3:0xde
	v_bitop3_b32 v201, v0, v1, v3 bitop3:0xde
	s_cselect_b32 s4, s4, 0xaa6410a1
	v_lshlrev_b32_e32 v0, 15, v9
	v_writelane_b32 v254, s4, 41
	s_add_u32 s4, s20, 0x3ee00000
	v_and_b32_e32 v0, 0xffff0000, v0
	s_addc_u32 s5, s21, 0
	v_lshl_add_u32 v0, v10, 12, v0
	v_and_b32_e32 v1, 1, v9
	s_add_u32 s6, s20, 0x40600000
	v_lshl_or_b32 v0, v1, 6, v0
	s_addc_u32 s7, s21, 0
	v_lshl_add_u32 v178, v11, 1, v0
	v_lshlrev_b32_e32 v0, 15, v12
	s_add_u32 s8, s20, 0x44380000
	v_and_b32_e32 v0, 0xffff0000, v0
	s_waitcnt vmcnt(6)
	s_addc_u32 s9, s21, 0
	v_lshl_add_u32 v0, v13, 12, v0
	v_and_b32_e32 v1, 1, v12
	v_writelane_b32 v254, s15, 42
	s_lshl_b32 s16, s15, 1
	v_lshl_or_b32 v0, v1, 6, v0
	v_writelane_b32 v254, s16, 44
	v_ashrrev_i32_e32 v200, 4, v8
	v_mov_b32_e32 v179, v64
	v_lshl_add_u32 v180, v14, 1, v0
	v_mov_b32_e32 v181, v64
	s_mov_b32 s85, 0
	v_add_u32_e32 v202, 0, v2
	v_writelane_b32 v254, s17, 45
	s_mov_b32 s34, s72
	s_barrier
	s_branch .LBB0_322
